# GEMM unit boundary: remaining accumulator zeroing done with 64 v_mov_b64 instead of 128 v_mov_b32 (on top of the redundant block removal)
# speedup vs baseline: 1.0064x; 1.0064x over previous
.LBB0_45:
	s_andn2_b64 vcc, exec, s[14:15]
	v_mov_b64_e32 v[0:1], 0
	v_mov_b64_e32 v[2:3], 0
	v_mov_b64_e32 v[4:5], 0
	v_mov_b64_e32 v[6:7], 0
	v_mov_b64_e32 v[8:9], 0
	v_mov_b64_e32 v[10:11], 0
	v_mov_b64_e32 v[12:13], 0
	v_mov_b64_e32 v[14:15], 0
	v_mov_b64_e32 v[16:17], 0
	v_mov_b64_e32 v[18:19], 0
	v_mov_b64_e32 v[20:21], 0
	v_mov_b64_e32 v[22:23], 0
	v_mov_b64_e32 v[24:25], 0
	v_mov_b64_e32 v[26:27], 0
	v_mov_b64_e32 v[28:29], 0
	v_mov_b64_e32 v[30:31], 0
	v_mov_b64_e32 v[32:33], 0
	v_mov_b64_e32 v[34:35], 0
	v_mov_b64_e32 v[36:37], 0
	v_mov_b64_e32 v[38:39], 0
	v_mov_b64_e32 v[40:41], 0
	v_mov_b64_e32 v[42:43], 0
	v_mov_b64_e32 v[44:45], 0
	v_mov_b64_e32 v[46:47], 0
	v_mov_b64_e32 v[48:49], 0
	v_mov_b64_e32 v[50:51], 0
	v_mov_b64_e32 v[52:53], 0
	v_mov_b64_e32 v[54:55], 0
	v_mov_b64_e32 v[56:57], 0
	v_mov_b64_e32 v[58:59], 0
	v_mov_b64_e32 v[60:61], 0
	v_mov_b64_e32 v[62:63], 0
	v_mov_b64_e32 v[64:65], 0
	v_mov_b64_e32 v[66:67], 0
	v_mov_b64_e32 v[68:69], 0
	v_mov_b64_e32 v[70:71], 0
	v_mov_b64_e32 v[72:73], 0
	v_mov_b64_e32 v[74:75], 0
	v_mov_b64_e32 v[76:77], 0
	v_mov_b64_e32 v[78:79], 0
	v_mov_b64_e32 v[80:81], 0
	v_mov_b64_e32 v[82:83], 0
	v_mov_b64_e32 v[84:85], 0
	v_mov_b64_e32 v[86:87], 0
	v_mov_b64_e32 v[88:89], 0
	v_mov_b64_e32 v[90:91], 0
	v_mov_b64_e32 v[92:93], 0
	v_mov_b64_e32 v[94:95], 0
	v_mov_b64_e32 v[96:97], 0
	v_mov_b64_e32 v[98:99], 0
	v_mov_b64_e32 v[100:101], 0
	v_mov_b64_e32 v[102:103], 0
	v_mov_b64_e32 v[104:105], 0
	v_mov_b64_e32 v[106:107], 0
	v_mov_b64_e32 v[108:109], 0
	v_mov_b64_e32 v[110:111], 0
	v_mov_b64_e32 v[112:113], 0
	v_mov_b64_e32 v[114:115], 0
	v_mov_b64_e32 v[116:117], 0
	v_mov_b64_e32 v[118:119], 0
	v_mov_b64_e32 v[120:121], 0
	v_mov_b64_e32 v[122:123], 0
	v_mov_b64_e32 v[124:125], 0
	v_mov_b64_e32 v[126:127], 0
	s_cbranch_vccnz .LBB0_49
	s_add_u32 s0, s28, 0x80
	s_addc_u32 s1, s29, 0
	s_add_u32 s28, s26, 0x100
	s_addc_u32 s29, s27, 0
	s_mov_b32 s26, 0

.LBB0_101:
	s_andn2_b64 vcc, exec, s[14:15]
	v_mov_b64_e32 v[0:1], 0
	v_mov_b64_e32 v[2:3], 0
	v_mov_b64_e32 v[4:5], 0
	v_mov_b64_e32 v[6:7], 0
	v_mov_b64_e32 v[8:9], 0
	v_mov_b64_e32 v[10:11], 0
	v_mov_b64_e32 v[12:13], 0
	v_mov_b64_e32 v[14:15], 0
	v_mov_b64_e32 v[16:17], 0
	v_mov_b64_e32 v[18:19], 0
	v_mov_b64_e32 v[20:21], 0
	v_mov_b64_e32 v[22:23], 0
	v_mov_b64_e32 v[24:25], 0
	v_mov_b64_e32 v[26:27], 0
	v_mov_b64_e32 v[28:29], 0
	v_mov_b64_e32 v[30:31], 0
	v_mov_b64_e32 v[32:33], 0
	v_mov_b64_e32 v[34:35], 0
	v_mov_b64_e32 v[36:37], 0
	v_mov_b64_e32 v[38:39], 0
	v_mov_b64_e32 v[40:41], 0
	v_mov_b64_e32 v[42:43], 0
	v_mov_b64_e32 v[44:45], 0
	v_mov_b64_e32 v[46:47], 0
	v_mov_b64_e32 v[48:49], 0
	v_mov_b64_e32 v[50:51], 0
	v_mov_b64_e32 v[52:53], 0
	v_mov_b64_e32 v[54:55], 0
	v_mov_b64_e32 v[56:57], 0
	v_mov_b64_e32 v[58:59], 0
	v_mov_b64_e32 v[60:61], 0
	v_mov_b64_e32 v[62:63], 0
	v_mov_b64_e32 v[64:65], 0
	v_mov_b64_e32 v[66:67], 0
	v_mov_b64_e32 v[68:69], 0
	v_mov_b64_e32 v[70:71], 0
	v_mov_b64_e32 v[72:73], 0
	v_mov_b64_e32 v[74:75], 0
	v_mov_b64_e32 v[76:77], 0
	v_mov_b64_e32 v[78:79], 0
	v_mov_b64_e32 v[80:81], 0
	v_mov_b64_e32 v[82:83], 0
	v_mov_b64_e32 v[84:85], 0
	v_mov_b64_e32 v[86:87], 0
	v_mov_b64_e32 v[88:89], 0
	v_mov_b64_e32 v[90:91], 0
	v_mov_b64_e32 v[92:93], 0
	v_mov_b64_e32 v[94:95], 0
	v_mov_b64_e32 v[96:97], 0
	v_mov_b64_e32 v[98:99], 0
	v_mov_b64_e32 v[100:101], 0
	v_mov_b64_e32 v[102:103], 0
	v_mov_b64_e32 v[104:105], 0
	v_mov_b64_e32 v[106:107], 0
	v_mov_b64_e32 v[108:109], 0
	v_mov_b64_e32 v[110:111], 0
	v_mov_b64_e32 v[112:113], 0
	v_mov_b64_e32 v[114:115], 0
	v_mov_b64_e32 v[116:117], 0
	v_mov_b64_e32 v[118:119], 0
	v_mov_b64_e32 v[120:121], 0
	v_mov_b64_e32 v[122:123], 0
	v_mov_b64_e32 v[124:125], 0
	v_mov_b64_e32 v[126:127], 0
	s_cbranch_vccnz .LBB0_105
	s_add_u32 s24, s24, 0x80
	s_addc_u32 s25, s25, 0
	s_add_u32 s54, s26, 0x100
	s_addc_u32 s55, s27, 0
	s_mov_b32 s26, 0
